# mixer item rotation keyed by (XCD + sub-group of 8 WGs) instead of XCD only, on stack22
# baseline (speedup 1.0000x reference)
; #define LAS __attribute__((address_space(3)))
; __device__ __forceinline__ void mixa_item(const Args& A, int li, int item, LAS unsigned char* lds, int tid, int lane, int wave) {
;     const int chunk = item >> 1, gh = item & 1, row0 = chunk * 128;
;     const bf16_t* UV = (const bf16_t*)(A.ws + WS_UV); bf16_t* CAT = (bf16_t*)(A.ws + WS_CAT);
;     const float* vg = A.in[8] + li * 512; const float* vb = A.in[9] + li * 512; const float* spb = A.in[7] + li * 8 * 128;
;     const bf16_t* spw = (const bf16_t*)(A.ws + WS_SPW) + (size_t)li * 8 * 128 * 128;
;     {
;         const int l15 = lane & 15, l4 = lane >> 4;
;         f32x4 gA[2][2], bA[2][2];
; #pragma unroll
;         for (int i = 0; i < 2; ++i) { const int chn = (l15 + 16 * (2 * gh + i)) * 8;
;             gA[i][0] = *(const f32x4*)(vg + chn); gA[i][1] = *(const f32x4*)(vg + chn + 4); bA[i][0] = *(const f32x4*)(vb + chn); bA[i][1] = *(const f32x4*)(vb + chn + 4); }
;         u32x4 w[4][4];
; #pragma unroll
;         for (int it = 0; it < 4; ++it)
; #pragma unroll
;             for (int i = 0; i < 4; ++i) w[it][i] = *(const u32x4*)(UV + (size_t)(row0 + wave * 16 + it * 4 + l4) * 1024 + 512 + (l15 + 16 * i) * 8);
;         u32x4 wsel[4][2];
; #pragma unroll
;         for (int it = 0; it < 4; ++it)
; #pragma unroll
;             for (int i = 0; i < 2; ++i) wsel[it][i] = *(const u32x4*)(UV + (size_t)(row0 + wave * 16 + it * 4 + l4) * 1024 + 512 + (l15 + 16 * (2 * gh + i)) * 8);
; #pragma unroll
; __global__ void __launch_bounds__(NTHR, 2) mega_fwd(Args A) {
;     ...
;         if (even) { for (int it = bx; it < 768; it += G) {
;     ...
;  if (it < 256) { mixa_item(A, li, it, lds, tid, lane, wave);
.LBB0_433:
	s_and_b64 vcc, exec, s[0:1]
	s_cbranch_vccz .LBB0_480
	v_readlane_b32 s0, v252, 51
	v_readlane_b32 s1, v252, 52
	s_andn2_b64 vcc, exec, s[0:1]
	s_cbranch_vccnz .LBB0_480
	v_readlane_b32 s0, v254, 24
	v_readlane_b32 s1, v254, 25
	v_readlane_b32 s4, v254, 52
	v_readlane_b32 s68, v252, 31
	s_mov_b32 s3, s1
	s_lshl_b32 s2, s4, 9
	v_readlane_b32 s69, v252, 32
	s_lshl_b64 s[48:49], s[2:3], 2
	v_readlane_b32 s70, v252, 33
	v_readlane_b32 s71, v252, 34
	v_readlane_b32 s72, v252, 35
	v_readlane_b32 s73, v252, 36
	v_readlane_b32 s74, v252, 37
	v_readlane_b32 s75, v252, 38
	v_readlane_b32 s76, v252, 39
	v_readlane_b32 s77, v252, 40
	v_readlane_b32 s78, v252, 41
	v_readlane_b32 s79, v252, 42
	s_mov_b64 s[52:53], s[68:69]
	s_add_u32 s8, s52, s48
	v_readlane_b32 s80, v252, 43
	v_readlane_b32 s81, v252, 44
	v_readlane_b32 s82, v252, 45
	v_readlane_b32 s83, v252, 46
	s_mov_b64 s[54:55], s[70:71]
	s_addc_u32 s9, s53, s49
	s_mov_b64 s[56:57], s[72:73]
	s_mov_b64 s[58:59], s[74:75]
	s_mov_b64 s[60:61], s[76:77]
	s_mov_b64 s[62:63], s[78:79]
	s_add_u32 s16, s54, s48
	v_readlane_b32 s68, v252, 15
	s_addc_u32 s17, s55, s49
	s_lshl_b32 s2, s4, 10
	v_writelane_b32 v254, s0, 24
	v_readlane_b32 s82, v252, 29
	v_readlane_b32 s83, v252, 30
	v_writelane_b32 v254, s1, 25
	s_lshl_b64 s[0:1], s[2:3], 2
	s_mov_b64 s[22:23], s[82:83]
	s_add_u32 s26, s22, s0
	v_lshrrev_b32_e32 v6, 4, v168
	v_readlane_b32 s2, v254, 55
	s_addc_u32 s27, s23, s1
	s_movk_i32 s1, 0x2a0
	s_waitcnt vmcnt(0)
	v_lshl_or_b32 v113, s2, 4, v6
	s_lshl_b32 s0, s4, 18
	v_mul_lo_u32 v9, v113, s1
	v_readlane_b32 s1, v254, 0
	s_add_u32 s0, s1, s0
	v_readlane_b32 s1, v254, 1
	v_bfe_u32 v2, v160, 2, 2
	s_addc_u32 s1, s1, 0
	v_lshl_or_b32 v2, v6, 2, v2
	s_and_b32 s4, s5, 0xffffff80
	v_lshlrev_b32_e32 v3, 3, v168
	v_mul_u32_u24_e32 v2, 0x2a0, v2
	v_and_b32_e32 v3, 24, v3
	s_add_i32 s4, s4, 0
	v_add3_u32 v115, s4, v2, v3
	v_lshlrev_b32_e32 v2, 3, v6
	v_mov_b32_e32 v3, v177
	v_lshl_add_u64 v[4:5], s[0:1], 0, v[2:3]
	v_readlane_b32 s0, v253, 49
	s_movk_i32 s10, 0x980
	v_readlane_b32 s1, v253, 50
	v_cmp_gt_i32_e64 s[38:39], s10, v160
	s_movk_i32 s10, 0x780
	v_lshl_add_u64 v[116:117], s[0:1], 0, v[2:3]
	v_readlane_b32 s0, v254, 2
	v_cmp_gt_i32_e64 s[40:41], s10, v160
	s_movk_i32 s10, 0x580
	v_readlane_b32 s1, v254, 3
	v_cmp_gt_i32_e64 s[42:43], s10, v160
	s_movk_i32 s10, 0x380
	s_ashr_i32 s3, s5, 7
	v_lshl_add_u64 v[118:119], s[0:1], 0, v[2:3]
	v_lshlrev_b32_e32 v155, 4, v160
	v_readlane_b32 s0, v253, 53
	v_cmp_gt_i32_e64 s[44:45], s10, v160
	s_movk_i32 s10, 0x180
	v_and_b32_e32 v2, 0x3f0, v155
	v_readlane_b32 s1, v253, 54
	v_cmp_gt_i32_e64 s[46:47], s10, v160
	s_add_u32 s10, s58, s48
	v_and_b32_e32 v25, 0xff, v160
	v_lshl_add_u64 v[120:121], s[0:1], 0, v[2:3]
	s_addc_u32 s11, s59, s49
	v_lshlrev_b32_e32 v2, 3, v25
	v_lshl_add_u64 v[122:123], s[10:11], 0, v[2:3]
	s_lshl_b32 s11, s2, 2
	s_and_b32 s10, s11, -16
	s_add_i32 s14, 0, 0x10000
	v_ashrrev_i32_e32 v157, 6, v161
	v_lshlrev_b32_e32 v11, 4, v161
	s_add_u32 s20, s60, s48
	v_or_b32_e32 v161, s11, v6
	s_movk_i32 s11, 0x810
	s_waitcnt lgkmcnt(0)
	v_and_b32_e32 v1, 15, v160
	s_addc_u32 s21, s61, s49
	v_mul_lo_u32 v6, v161, s11
	v_lshlrev_b32_e32 v112, 3, v1
	v_lshlrev_b32_e32 v0, 4, v1
	s_waitcnt lgkmcnt(0)
	v_and_or_b32 v114, s5, 64, v1
	s_movk_i32 s4, 0xd80
	v_add_u32_e32 v26, s14, v6
	s_add_u32 s22, s62, s48
	v_lshlrev_b32_e32 v6, 2, v1
	v_mov_b32_e32 v1, v177
	s_movk_i32 s0, 0xf80
	v_cmp_gt_i32_e64 s[6:7], s4, v160
	s_movk_i32 s4, 0xb80
	s_addc_u32 s23, s63, s49
	v_lshl_add_u64 v[124:125], s[20:21], 0, v[0:1]
	s_lshr_b64 s[20:21], s[18:19], 1
	s_lshr_b32 s11, s19, 1
	v_ashrrev_i32_e32 v156, 6, v160
	v_cmp_gt_i32_e64 s[0:1], s0, v160
	v_cmp_gt_i32_e64 s[4:5], s4, v160
	v_add_u32_e32 v160, s14, v2
	s_mul_i32 s11, s11, 0xf800
	s_mul_hi_u32 s14, s20, 0xf800
	s_add_i32 s14, s14, s11
	s_mul_i32 s11, s20, 0xf800
	s_add_u32 s20, s56, s11
	s_addc_u32 s21, s57, s14
	s_lshl_b32 s2, s2, 12
	s_and_b32 s2, s2, 0xffffc000
	v_add_u32_e32 v7, 0, v0
	v_lshlrev_b32_e32 v13, 4, v162
	v_lshlrev_b32_e32 v15, 4, v163
	v_lshlrev_b32_e32 v17, 4, v164
	v_lshlrev_b32_e32 v19, 4, v165
	v_lshlrev_b32_e32 v21, 4, v166
	v_lshlrev_b32_e32 v24, 4, v167
	v_or_b32_e32 v8, 64, v6
	v_or_b32_e32 v10, 0x80, v6
	v_or_b32_e32 v12, 0xc0, v6
	v_or_b32_e32 v14, 0x100, v6
	v_or_b32_e32 v16, 0x140, v6
	v_or_b32_e32 v18, 0x180, v6
	v_or_b32_e32 v20, 0x1c0, v6
	v_lshlrev_b32_e32 v22, 8, v114
	v_mov_b32_e32 v23, v177
	s_add_i32 s2, s2, 0
	v_add_u32_e32 v148, 0x12600, v115
	v_add_u32_e32 v149, 0x12620, v115
	v_add_u32_e32 v150, 0x12640, v115
	v_add_u32_e32 v151, 0x12660, v115
	v_or_b32_e32 v152, 16, v114
	v_or_b32_e32 v153, 32, v114
	v_or_b32_e32 v154, 48, v114
	v_ashrrev_i32_e32 v158, 6, v162
	v_ashrrev_i32_e32 v159, 6, v163
	v_ashrrev_i32_e32 v168, 6, v164
	v_ashrrev_i32_e32 v169, 6, v165
	v_ashrrev_i32_e32 v170, 6, v166
	v_ashrrev_i32_e32 v171, 6, v167
	v_lshl_add_u64 v[126:127], s[22:23], 0, v[0:1]
	v_lshl_add_u64 v[128:129], v[4:5], 0, v[22:23]
	v_lshl_add_u64 v[130:131], s[20:21], 0, v[2:3]
	v_lshl_add_u32 v162, v25, 2, s2
	v_add_u32_e32 v163, v7, v9
	v_add_u32_e32 v164, 0, v11
	v_add_u32_e32 v165, 0, v13
	v_add_u32_e32 v166, 0, v15
	v_add_u32_e32 v167, 0, v17
	v_add_u32_e32 v172, 0, v19
	v_add_u32_e32 v173, 0, v21
	v_add_u32_e32 v174, 0, v24
	v_add_u32_e32 v175, v26, v0
	v_lshlrev_b32_e32 v132, 1, v6
	v_lshlrev_b32_e32 v134, 1, v8
	v_lshlrev_b32_e32 v136, 1, v10
	v_lshlrev_b32_e32 v138, 1, v12
	v_lshlrev_b32_e32 v140, 1, v14
	v_lshlrev_b32_e32 v142, 1, v16
	v_lshlrev_b32_e32 v144, 1, v18
	v_lshlrev_b32_e32 v146, 1, v20
	s_mov_b32 s2, s67
	s_mov_b32 s101, 0
	v_readlane_b32 s100, v252, 10
	s_cmp_lg_u32 s100, 0x100
	s_cbranch_scc1 .Lxr_plain
	s_and_b32 s100, s67, 7
	s_lshr_b32 s101, s67, 6
	s_add_i32 s100, s100, s101
	s_mul_i32 s101, s100, 11
	s_lshr_b32 s101, s101, 5
	s_mul_i32 s101, s101, 3
	s_sub_i32 s100, s100, s101
	s_lshl_b32 s100, s100, 8
	s_add_i32 s2, s67, s100
	s_mov_b32 s101, 3
